# v11 + norm phases 4, 8, 11, 14: next latent row's loads stay in flight during the current row's arithmetic (convert after the row's stores behind vmcnt(4)) instead of being waited for right after issu
# baseline (speedup 1.0000x reference)
; __device__ __forceinline__ void lds_barrier() { asm volatile("s_waitcnt lgkmcnt(0)" ::: "memory"); __builtin_amdgcn_s_barrier(); asm volatile("" ::: "memory"); }
; template <bool COMBINE, bool SRC_F32>
; __device__ __forceinline__ void norm_phase(LAS unsigned char* lds, const void* src_lat, const void* src_ctx, _Float16* xw_ctx, const float* part, int nrows, const float* g, const float* modl, int shift_idx, int scale_idx, bf16* HN, int tid, int lane, int wave) {
;     ...
;     if (gw < nrows) NORM_LOAD(v, gw);
;     lds_barrier();
;     for (int row = gw; row < nrows; row += NGW) {
;         if (row + NGW < nrows) NORM_LOAD(nv, row + NGW);
.LBB0_467:
	s_add_i32 s14, s6, s8
	s_add_i32 s0, s14, 0x4000
	s_cmpk_gt_i32 s0, 0x47ff
	s_cselect_b64 s[12:13], -1, 0
	s_and_b64 vcc, exec, s[12:13]
	s_cbranch_vccnz .LBB0_470
	s_ashr_i32 s1, s0, 31
	s_cmpk_lt_i32 s0, 0x4000
	s_cselect_b64 s[16:17], -1, 0
	s_and_b64 vcc, s[16:17], exec
	v_readlane_b32 s16, v253, 52
	v_readlane_b32 s17, v253, 53
	s_cselect_b32 s1, s1, 0
	s_cselect_b32 s0, s0, s14
	s_cselect_b32 s15, s17, s5
	s_cselect_b32 s18, s16, s4
	s_lshl_b64 s[16:17], s[0:1], 12
	s_add_u32 s16, s18, s16
	s_addc_u32 s17, s15, s17
	v_lshlrev_b32_e32 v2, 1, v66
	global_load_dwordx4 v[8:11], v2, s[16:17]
	global_load_dwordx4 v[16:19], v2, s[16:17] offset:1024
	global_load_dwordx4 v[24:27], v2, s[16:17] offset:2048
	global_load_dwordx4 v[120:123], v2, s[16:17] offset:3072
	s_cbranch_vccnz .LBB0_470
	s_waitcnt vmcnt(3)
	v_cvt_f32_f16_e32 v4, v9
	v_cvt_f32_f16_e32 v2, v8
	v_cvt_f32_f16_sdwa v5, v9 dst_sel:DWORD dst_unused:UNUSED_PAD src0_sel:WORD_1
	v_cvt_f32_f16_sdwa v3, v8 dst_sel:DWORD dst_unused:UNUSED_PAD src0_sel:WORD_1
	v_cvt_f32_f16_e32 v8, v11
	v_cvt_f32_f16_e32 v6, v10
	v_cvt_f32_f16_sdwa v9, v11 dst_sel:DWORD dst_unused:UNUSED_PAD src0_sel:WORD_1
	v_cvt_f32_f16_sdwa v7, v10 dst_sel:DWORD dst_unused:UNUSED_PAD src0_sel:WORD_1
	s_waitcnt vmcnt(2)
	v_cvt_f32_f16_e32 v12, v17
	v_cvt_f32_f16_e32 v10, v16
	v_cvt_f32_f16_sdwa v13, v17 dst_sel:DWORD dst_unused:UNUSED_PAD src0_sel:WORD_1
	v_cvt_f32_f16_sdwa v11, v16 dst_sel:DWORD dst_unused:UNUSED_PAD src0_sel:WORD_1
	v_cvt_f32_f16_e32 v16, v19
	v_cvt_f32_f16_e32 v14, v18
	v_cvt_f32_f16_sdwa v17, v19 dst_sel:DWORD dst_unused:UNUSED_PAD src0_sel:WORD_1
	v_cvt_f32_f16_sdwa v15, v18 dst_sel:DWORD dst_unused:UNUSED_PAD src0_sel:WORD_1
	s_waitcnt vmcnt(1)
	v_cvt_f32_f16_e32 v20, v25
	v_cvt_f32_f16_e32 v18, v24
	v_cvt_f32_f16_sdwa v21, v25 dst_sel:DWORD dst_unused:UNUSED_PAD src0_sel:WORD_1
	v_cvt_f32_f16_sdwa v19, v24 dst_sel:DWORD dst_unused:UNUSED_PAD src0_sel:WORD_1
	v_cvt_f32_f16_e32 v24, v27
	v_cvt_f32_f16_e32 v22, v26
	v_cvt_f32_f16_sdwa v25, v27 dst_sel:DWORD dst_unused:UNUSED_PAD src0_sel:WORD_1
	v_cvt_f32_f16_sdwa v23, v26 dst_sel:DWORD dst_unused:UNUSED_PAD src0_sel:WORD_1
	s_waitcnt vmcnt(0)
	v_cvt_f32_f16_e32 v28, v121
	v_cvt_f32_f16_e32 v26, v120
	v_cvt_f32_f16_sdwa v29, v121 dst_sel:DWORD dst_unused:UNUSED_PAD src0_sel:WORD_1
	v_cvt_f32_f16_sdwa v27, v120 dst_sel:DWORD dst_unused:UNUSED_PAD src0_sel:WORD_1
	v_cvt_f32_f16_e32 v32, v123
	v_cvt_f32_f16_e32 v30, v122
	v_cvt_f32_f16_sdwa v33, v123 dst_sel:DWORD dst_unused:UNUSED_PAD src0_sel:WORD_1
	v_cvt_f32_f16_sdwa v31, v122 dst_sel:DWORD dst_unused:UNUSED_PAD src0_sel:WORD_1
	s_lshl_b64 s[0:1], s[0:1], 11
	s_lshl_b64 s[0:1], s[0:1], 2
	v_readlane_b32 s15, v253, 54
	s_add_u32 s0, s15, s0
	v_readlane_b32 s15, v253, 56
	s_addc_u32 s1, s15, s1
	s_add_u32 s16, s0, 0x1000000
	v_lshlrev_b32_e32 v72, 2, v66
	s_addc_u32 s17, s1, 0
	global_load_dwordx4 v[80:83], v72, s[0:1] offset:16
	global_load_dwordx4 v[84:87], v72, s[0:1]
	global_load_dwordx4 v[88:91], v72, s[16:17]
	global_load_dwordx4 v[92:95], v72, s[16:17] offset:16
	global_load_dwordx4 v[96:99], v72, s[0:1] offset:2064
	global_load_dwordx4 v[100:103], v72, s[0:1] offset:2048
	global_load_dwordx4 v[104:107], v75, s[16:17]
	global_load_dwordx4 v[108:111], v75, s[16:17] offset:16
	global_load_dwordx4 v[112:115], v73, s[0:1] offset:16
	global_load_dwordx4 v[116:119], v73, s[0:1]
	global_load_dwordx4 v[120:123], v73, s[16:17]
	global_load_dwordx4 v[124:127], v73, s[16:17] offset:16
	global_load_dwordx4 v[128:131], v74, s[0:1] offset:16
	global_load_dwordx4 v[132:135], v74, s[0:1]
	global_load_dwordx4 v[136:139], v74, s[16:17]
	global_load_dwordx4 v[140:143], v74, s[16:17] offset:16
	s_add_u32 s0, s0, 0x2000000
	s_addc_u32 s1, s1, 0
	global_load_dwordx4 v[144:147], v72, s[0:1]
	global_load_dwordx4 v[148:151], v72, s[0:1] offset:16
	global_load_dwordx4 v[152:155], v75, s[0:1]
	global_load_dwordx4 v[156:159], v75, s[0:1] offset:16
	global_load_dwordx4 v[160:163], v73, s[0:1]
	global_load_dwordx4 v[164:167], v73, s[0:1] offset:16
	global_load_dwordx4 v[168:171], v74, s[0:1]
	global_load_dwordx4 v[172:175], v74, s[0:1] offset:16
	s_waitcnt vmcnt(20)
	v_pk_add_f32 v[82:83], v[82:83], v[94:95]
	v_pk_add_f32 v[86:87], v[86:87], v[90:91]
	v_pk_add_f32 v[84:85], v[84:85], v[88:89]
	v_pk_add_f32 v[80:81], v[80:81], v[92:93]
	s_waitcnt vmcnt(17)
	v_pk_add_f32 v[88:89], v[102:103], v[106:107]
	v_pk_add_f32 v[90:91], v[100:101], v[104:105]
	s_waitcnt vmcnt(16)
	v_pk_add_f32 v[92:93], v[98:99], v[110:111]
	v_pk_add_f32 v[94:95], v[96:97], v[108:109]
	s_waitcnt vmcnt(13)
	v_pk_add_f32 v[96:97], v[118:119], v[122:123]
	v_pk_add_f32 v[98:99], v[116:117], v[120:121]
	s_waitcnt vmcnt(12)
	v_pk_add_f32 v[100:101], v[114:115], v[126:127]
	v_pk_add_f32 v[102:103], v[112:113], v[124:125]
	s_waitcnt vmcnt(9)
	v_pk_add_f32 v[104:105], v[134:135], v[138:139]
	v_pk_add_f32 v[106:107], v[132:133], v[136:137]
	s_waitcnt vmcnt(8)
	v_pk_add_f32 v[108:109], v[130:131], v[142:143]
	v_pk_add_f32 v[110:111], v[128:129], v[140:141]
	s_waitcnt vmcnt(7)
	v_pk_add_f32 v[86:87], v[86:87], v[146:147]
	v_pk_add_f32 v[84:85], v[84:85], v[144:145]
	s_waitcnt vmcnt(6)
	v_pk_add_f32 v[82:83], v[82:83], v[150:151]
	v_pk_add_f32 v[80:81], v[80:81], v[148:149]
	s_waitcnt vmcnt(5)
	v_pk_add_f32 v[88:89], v[88:89], v[154:155]
	v_pk_add_f32 v[90:91], v[90:91], v[152:153]
	s_waitcnt vmcnt(4)
	v_pk_add_f32 v[92:93], v[92:93], v[158:159]
	v_pk_add_f32 v[94:95], v[94:95], v[156:157]
	s_waitcnt vmcnt(3)
	v_pk_add_f32 v[96:97], v[96:97], v[162:163]
	v_pk_add_f32 v[98:99], v[98:99], v[160:161]
	s_waitcnt vmcnt(2)
	v_pk_add_f32 v[100:101], v[100:101], v[166:167]
	v_pk_add_f32 v[102:103], v[102:103], v[164:165]
	s_waitcnt vmcnt(1)
	v_pk_add_f32 v[104:105], v[104:105], v[170:171]
	v_pk_add_f32 v[106:107], v[106:107], v[168:169]
	s_waitcnt vmcnt(0)
	v_pk_add_f32 v[108:109], v[108:109], v[174:175]
	v_pk_add_f32 v[110:111], v[110:111], v[172:173]
	v_pk_add_f32 v[4:5], v[86:87], v[4:5]
	v_pk_add_f32 v[2:3], v[84:85], v[2:3]
	v_pk_add_f32 v[8:9], v[82:83], v[8:9]
	v_pk_add_f32 v[6:7], v[80:81], v[6:7]
	v_pk_add_f32 v[12:13], v[88:89], v[12:13]
	v_pk_add_f32 v[10:11], v[90:91], v[10:11]
	v_pk_add_f32 v[16:17], v[92:93], v[16:17]
	v_pk_add_f32 v[14:15], v[94:95], v[14:15]
	v_pk_add_f32 v[20:21], v[96:97], v[20:21]
	v_pk_add_f32 v[18:19], v[98:99], v[18:19]
	v_pk_add_f32 v[24:25], v[100:101], v[24:25]
	v_pk_add_f32 v[22:23], v[102:103], v[22:23]
	v_pk_add_f32 v[28:29], v[104:105], v[28:29]
	v_pk_add_f32 v[26:27], v[106:107], v[26:27]
	v_pk_add_f32 v[32:33], v[108:109], v[32:33]
	v_pk_add_f32 v[30:31], v[110:111], v[30:31]
; #define LAS __attribute__((address_space(3)))
; __device__ __forceinline__ f32x4 h4_to_f32x4(u32x2 v) { return __builtin_convertvector(__builtin_bit_cast(f16x4, v), f32x4); }
; template <bool COMBINE, bool SRC_F32>
; __device__ __forceinline__ void norm_phase(LAS unsigned char* lds, const void* src_lat, const void* src_ctx, _Float16* xw_ctx, const float* part, int nrows, const float* g, const float* modl, int shift_idx, int scale_idx, bf16* HN, int tid, int lane, int wave) {
;     ...
;         const int r = row < M_LAT ? (row >> 11) : 8;
;         float ss = 0.f;
; #pragma unroll
;         for (int j = 0; j < 8; ++j) ss += (v[j][0] * v[j][0] + v[j][1] * v[j][1]) + (v[j][2] * v[j][2] + v[j][3] * v[j][3]);
;         const float rstd = 1.0f / sqrtf(wave_sum_dpp(ss) * (1.0f / D) + EPS);
;         bf16* o = HN + (size_t)row * D;
;         f32x4 y[8];
; #pragma unroll
;         for (int j = 0; j < 8; ++j) { const int c = NORM_COL(j); y[j] = (v[j] * rstd) * h4_to_f32x4(*(const LAS u32x2*)(Gs + r * D + c)) + h4_to_f32x4(*(const LAS u32x2*)(Ss + r * D + c)); }
.LBB0_470:
	v_mul_f32_e32 v72, v35, v35
	v_mul_f32_e32 v79, v37, v37
	v_fmac_f32_e32 v72, v34, v34
	v_fmac_f32_e32 v79, v36, v36
	v_add_f32_e32 v72, v72, v79
	v_mul_f32_e32 v79, v39, v39
	v_mul_f32_e32 v80, v41, v41
	v_fmac_f32_e32 v79, v38, v38
	v_fmac_f32_e32 v80, v40, v40
	v_add_f32_e32 v79, v79, v80
	v_add_f32_e32 v72, v72, v79
	v_mul_f32_e32 v79, v43, v43
	v_mul_f32_e32 v80, v45, v45
	v_fmac_f32_e32 v79, v42, v42
	v_fmac_f32_e32 v80, v44, v44
	v_add_f32_e32 v79, v79, v80
	v_add_f32_e32 v72, v79, v72
	v_mul_f32_e32 v79, v47, v47
	v_mul_f32_e32 v80, v49, v49
	v_fmac_f32_e32 v79, v46, v46
	v_fmac_f32_e32 v80, v48, v48
	v_add_f32_e32 v79, v79, v80
	v_add_f32_e32 v72, v79, v72
	v_mul_f32_e32 v79, v51, v51
	v_mul_f32_e32 v80, v53, v53
	v_fmac_f32_e32 v79, v50, v50
	v_fmac_f32_e32 v80, v52, v52
	v_add_f32_e32 v79, v79, v80
	v_add_f32_e32 v72, v79, v72
	v_mul_f32_e32 v79, v55, v55
	v_mul_f32_e32 v80, v57, v57
	v_fmac_f32_e32 v79, v54, v54
	v_fmac_f32_e32 v80, v56, v56
	v_add_f32_e32 v79, v79, v80
	v_add_f32_e32 v72, v79, v72
	v_mul_f32_e32 v79, v59, v59
	v_mul_f32_e32 v80, v61, v61
	v_fmac_f32_e32 v79, v58, v58
	v_fmac_f32_e32 v80, v60, v60
	v_add_f32_e32 v79, v79, v80
	v_add_f32_e32 v72, v79, v72
	v_mul_f32_e32 v79, v63, v63
	v_mul_f32_e32 v80, v65, v65
	v_fmac_f32_e32 v79, v62, v62
	v_fmac_f32_e32 v80, v64, v64
	v_add_f32_e32 v79, v79, v80
	v_add_f32_e32 v72, v79, v72
	v_mov_b32_e32 v79, 0
	s_nop 0
	v_add_f32_dpp v72, v72, v72 quad_perm:[1,0,3,2] row_mask:0xf bank_mask:0xf bound_ctrl:1
	s_nop 1
	v_add_f32_dpp v72, v72, v72 quad_perm:[2,3,0,1] row_mask:0xf bank_mask:0xf bound_ctrl:1
	s_nop 1
	v_add_f32_dpp v72, v72, v72 row_half_mirror row_mask:0xf bank_mask:0xf bound_ctrl:1
	s_nop 1
	v_add_f32_dpp v72, v72, v72 row_mirror row_mask:0xf bank_mask:0xf bound_ctrl:1
	s_nop 1
	v_mov_b32_dpp v79, v72 row_bcast:15 row_mask:0xa bank_mask:0xf
	v_add_f32_e32 v72, v72, v79
	v_mov_b32_e32 v79, 0
	s_nop 1
	v_mov_b32_dpp v79, v72 row_bcast:31 row_mask:0xc bank_mask:0xf
	v_add_f32_e32 v72, v72, v79
	s_nop 0
	v_readlane_b32 s0, v72, 63
	s_nop 1
	v_fma_f32 v72, s0, v78, v76
	v_mul_f32_e32 v79, 0x4f800000, v72
	v_cmp_gt_f32_e32 vcc, s7, v72
	s_nop 1
	v_cndmask_b32_e32 v72, v72, v79, vcc
	v_sqrt_f32_e32 v79, v72
	s_nop 0
	v_add_u32_e32 v80, -1, v79
	v_fma_f32 v81, -v80, v79, v72
	v_cmp_ge_f32_e64 s[0:1], 0, v81
	v_add_u32_e32 v81, 1, v79
	s_nop 0
	v_cndmask_b32_e64 v80, v79, v80, s[0:1]
	v_fma_f32 v79, -v81, v79, v72
	v_cmp_lt_f32_e64 s[0:1], 0, v79
	s_nop 1
	v_cndmask_b32_e64 v79, v80, v81, s[0:1]
	v_mul_f32_e32 v80, 0x37800000, v79
	v_cndmask_b32_e32 v79, v79, v80, vcc
	v_cmp_class_f32_e32 vcc, v72, v77
	s_nop 1
	v_cndmask_b32_e32 v72, v79, v72, vcc
	v_div_scale_f32 v79, s[0:1], v72, v72, 1.0
	v_rcp_f32_e32 v84, v79
	s_add_i32 s0, s8, 0x4000
	s_min_i32 s1, s0, 0x4000
	s_and_b32 s1, s1, 0x7ffff800
	v_fma_f32 v80, -v79, v84, 1.0
	v_fmac_f32_e32 v84, v80, v84
	v_div_scale_f32 v80, vcc, 1.0, v72, 1.0
	v_mul_f32_e32 v85, v80, v84
	v_fma_f32 v81, -v79, v85, v80
	v_fmac_f32_e32 v85, v81, v84
	v_lshl_add_u32 v114, s1, 1, v67
	v_fma_f32 v79, -v79, v85, v80
	ds_read_b128 v[80:83], v114
	ds_read_b128 v[88:91], v114 offset:36864
	ds_read_b128 v[92:95], v114 offset:37888
	v_div_fmas_f32 v79, v79, v84, v85
	ds_read_b128 v[84:87], v114 offset:1024
	s_waitcnt lgkmcnt(3)
	v_cvt_f32_f16_e32 v96, v80
	v_cvt_f32_f16_sdwa v97, v80 dst_sel:DWORD dst_unused:UNUSED_PAD src0_sel:WORD_1
	v_cvt_f32_f16_e32 v80, v81
	v_cvt_f32_f16_sdwa v81, v81 dst_sel:DWORD dst_unused:UNUSED_PAD src0_sel:WORD_1
	s_waitcnt lgkmcnt(2)
	v_cvt_f32_f16_e32 v98, v88
	v_cvt_f32_f16_e32 v100, v89
	v_cvt_f32_f16_sdwa v101, v89 dst_sel:DWORD dst_unused:UNUSED_PAD src0_sel:WORD_1
	v_cvt_f32_f16_sdwa v99, v88 dst_sel:DWORD dst_unused:UNUSED_PAD src0_sel:WORD_1
	v_div_fixup_f32 v72, v79, v72, 1.0
	v_pk_mul_f32 v[88:89], v[34:35], v[72:73] op_sel_hi:[1,0]
	v_pk_mul_f32 v[102:103], v[36:37], v[72:73] op_sel_hi:[1,0]
	v_pk_fma_f32 v[96:97], v[88:89], v[96:97], v[98:99]
	v_pk_fma_f32 v[100:101], v[102:103], v[80:81], v[100:101]
	v_cvt_f32_f16_e32 v80, v82
	v_cvt_f32_f16_sdwa v81, v82 dst_sel:DWORD dst_unused:UNUSED_PAD src0_sel:WORD_1
	v_cvt_f32_f16_e32 v82, v83
	v_cvt_f32_f16_sdwa v83, v83 dst_sel:DWORD dst_unused:UNUSED_PAD src0_sel:WORD_1
	v_cvt_f32_f16_e32 v88, v90
	v_cvt_f32_f16_e32 v98, v91
	v_cvt_f32_f16_sdwa v99, v91 dst_sel:DWORD dst_unused:UNUSED_PAD src0_sel:WORD_1
	v_cvt_f32_f16_sdwa v89, v90 dst_sel:DWORD dst_unused:UNUSED_PAD src0_sel:WORD_1
	v_pk_mul_f32 v[90:91], v[38:39], v[72:73] op_sel_hi:[1,0]
	v_pk_mul_f32 v[102:103], v[40:41], v[72:73] op_sel_hi:[1,0]
	v_pk_mul_f32 v[118:119], v[52:53], v[72:73] op_sel_hi:[1,0]
	v_pk_fma_f32 v[98:99], v[102:103], v[82:83], v[98:99]
	v_pk_fma_f32 v[102:103], v[90:91], v[80:81], v[88:89]
	s_waitcnt lgkmcnt(0)
	v_cvt_f32_f16_e32 v80, v84
	v_cvt_f32_f16_sdwa v81, v84 dst_sel:DWORD dst_unused:UNUSED_PAD src0_sel:WORD_1
	v_cvt_f32_f16_e32 v82, v85
	v_cvt_f32_f16_sdwa v83, v85 dst_sel:DWORD dst_unused:UNUSED_PAD src0_sel:WORD_1
	v_cvt_f32_f16_e32 v84, v92
	v_cvt_f32_f16_e32 v88, v93
	v_cvt_f32_f16_sdwa v89, v93 dst_sel:DWORD dst_unused:UNUSED_PAD src0_sel:WORD_1
	v_cvt_f32_f16_sdwa v85, v92 dst_sel:DWORD dst_unused:UNUSED_PAD src0_sel:WORD_1
	v_pk_mul_f32 v[90:91], v[42:43], v[72:73] op_sel_hi:[1,0]
	v_pk_mul_f32 v[92:93], v[44:45], v[72:73] op_sel_hi:[1,0]
	s_cmpk_lt_i32 s0, 0x4000
	v_pk_fma_f32 v[104:105], v[92:93], v[82:83], v[88:89]
	v_pk_fma_f32 v[106:107], v[90:91], v[80:81], v[84:85]
	v_cvt_f32_f16_e32 v88, v86
	v_cvt_f32_f16_sdwa v89, v86 dst_sel:DWORD dst_unused:UNUSED_PAD src0_sel:WORD_1
	v_cvt_f32_f16_e32 v90, v94
	v_cvt_f32_f16_sdwa v91, v94 dst_sel:DWORD dst_unused:UNUSED_PAD src0_sel:WORD_1
	v_pk_mul_f32 v[84:85], v[46:47], v[72:73] op_sel_hi:[1,0]
	ds_read_b128 v[80:83], v114 offset:2048
	v_cvt_f32_f16_e32 v86, v87
	v_pk_fma_f32 v[110:111], v[84:85], v[88:89], v[90:91]
	ds_read_b128 v[88:91], v114 offset:38912
	v_cvt_f32_f16_sdwa v87, v87 dst_sel:DWORD dst_unused:UNUSED_PAD src0_sel:WORD_1
	v_cvt_f32_f16_e32 v92, v95
	v_cvt_f32_f16_sdwa v93, v95 dst_sel:DWORD dst_unused:UNUSED_PAD src0_sel:WORD_1
	v_pk_mul_f32 v[94:95], v[48:49], v[72:73] op_sel_hi:[1,0]
	s_nop 0
	v_pk_fma_f32 v[108:109], v[94:95], v[86:87], v[92:93]
	ds_read_b128 v[84:87], v114 offset:3072
	s_waitcnt lgkmcnt(2)
; __device__ __forceinline__ unsigned cvt_pk_bf16(float lo, float hi) { unsigned r; asm volatile("v_cvt_pk_bf16_f32 %0, %1, %2" : "=v"(r) : "v"(lo), "v"(hi)); return r; }
; #define LAS __attribute__((address_space(3)))
; __device__ __forceinline__ u32x2 f32x4_to_h4(f32x4 v) { return __builtin_bit_cast(u32x2, __builtin_convertvector(v, f16x4)); }
; __device__ __forceinline__ f32x4 h4_to_f32x4(u32x2 v) { return __builtin_convertvector(__builtin_bit_cast(f16x4, v), f32x4); }
; template <bool COMBINE, bool SRC_F32>
; __device__ __forceinline__ void norm_phase(LAS unsigned char* lds, const void* src_lat, const void* src_ctx, _Float16* xw_ctx, const float* part, int nrows, const float* g, const float* modl, int shift_idx, int scale_idx, bf16* HN, int tid, int lane, int wave) {
;     ...
;         for (int j = 0; j < 8; ++j) { const int c = NORM_COL(j); y[j] = (v[j] * rstd) * h4_to_f32x4(*(const LAS u32x2*)(Gs + r * D + c)) + h4_to_f32x4(*(const LAS u32x2*)(Ss + r * D + c)); }
;         if constexpr (SRC_F32) {
; #pragma unroll
;             for (int j = 0; j < 8; ++j) { u32x2 w; w.x = pg8::cvt_pk_bf16(y[j][0], y[j][1]); w.y = pg8::cvt_pk_bf16(y[j][2], y[j][3]); *(u32x2*)(o + NORM_COL(j)) = w; }
;         } else {
; #pragma unroll
;             for (int j = 0; j < 4; ++j) { u32x4 w; w.x = pg8::cvt_pk_bf16(y[2 * j][0], y[2 * j][1]); w.y = pg8::cvt_pk_bf16(y[2 * j][2], y[2 * j][3]); w.z = pg8::cvt_pk_bf16(y[2 * j + 1][0], y[2 * j + 1][1]); w.w = pg8::cvt_pk_bf16(y[2 * j + 1][2], y[2 * j + 1][3]);
;                 *(u32x4*)(o + NORM_COL(2 * j)) = w; }
;         }
;         if (COMBINE && row >= M_LAT) {
; #pragma unroll
;             for (int j = 0; j < 4; ++j) { const u32x2 h0 = f32x4_to_h4(v[2 * j]), h1 = f32x4_to_h4(v[2 * j + 1]); *(u32x4*)(xw_ctx + (size_t)(row - M_LAT) * D + NORM_COL(2 * j)) = (u32x4){h0.x, h0.y, h1.x, h1.y}; }
;         }
	v_cvt_f32_f16_e32 v112, v80
	v_cvt_f32_f16_sdwa v113, v80 dst_sel:DWORD dst_unused:UNUSED_PAD src0_sel:WORD_1
	v_cvt_f32_f16_e32 v80, v81
	v_cvt_f32_f16_sdwa v81, v81 dst_sel:DWORD dst_unused:UNUSED_PAD src0_sel:WORD_1
	ds_read_b128 v[92:95], v114 offset:39936
	s_waitcnt lgkmcnt(2)
	v_cvt_f32_f16_e32 v114, v88
	v_cvt_f32_f16_e32 v116, v89
	v_cvt_f32_f16_sdwa v117, v89 dst_sel:DWORD dst_unused:UNUSED_PAD src0_sel:WORD_1
	v_cvt_f32_f16_sdwa v115, v88 dst_sel:DWORD dst_unused:UNUSED_PAD src0_sel:WORD_1
	v_pk_mul_f32 v[88:89], v[50:51], v[72:73] op_sel_hi:[1,0]
	v_pk_fma_f32 v[116:117], v[118:119], v[80:81], v[116:117]
	v_pk_fma_f32 v[88:89], v[88:89], v[112:113], v[114:115]
	v_cvt_f32_f16_e32 v80, v82
	v_cvt_f32_f16_sdwa v81, v82 dst_sel:DWORD dst_unused:UNUSED_PAD src0_sel:WORD_1
	v_cvt_f32_f16_e32 v82, v83
	v_cvt_f32_f16_sdwa v83, v83 dst_sel:DWORD dst_unused:UNUSED_PAD src0_sel:WORD_1
	v_cvt_f32_f16_e32 v112, v90
	v_cvt_f32_f16_e32 v114, v91
	v_cvt_f32_f16_sdwa v115, v91 dst_sel:DWORD dst_unused:UNUSED_PAD src0_sel:WORD_1
	v_cvt_f32_f16_sdwa v113, v90 dst_sel:DWORD dst_unused:UNUSED_PAD src0_sel:WORD_1
	v_pk_mul_f32 v[90:91], v[54:55], v[72:73] op_sel_hi:[1,0]
	v_pk_mul_f32 v[118:119], v[56:57], v[72:73] op_sel_hi:[1,0]
	v_pk_fma_f32 v[90:91], v[90:91], v[80:81], v[112:113]
	v_pk_fma_f32 v[114:115], v[118:119], v[82:83], v[114:115]
	s_waitcnt lgkmcnt(1)
	v_cvt_f32_f16_e32 v80, v84
	v_cvt_f32_f16_sdwa v81, v84 dst_sel:DWORD dst_unused:UNUSED_PAD src0_sel:WORD_1
	v_cvt_f32_f16_e32 v82, v85
	v_cvt_f32_f16_sdwa v83, v85 dst_sel:DWORD dst_unused:UNUSED_PAD src0_sel:WORD_1
	s_waitcnt lgkmcnt(0)
	v_cvt_f32_f16_e32 v84, v92
	v_cvt_f32_f16_e32 v112, v93
	v_cvt_f32_f16_sdwa v113, v93 dst_sel:DWORD dst_unused:UNUSED_PAD src0_sel:WORD_1
	v_cvt_f32_f16_sdwa v85, v92 dst_sel:DWORD dst_unused:UNUSED_PAD src0_sel:WORD_1
	v_pk_mul_f32 v[92:93], v[58:59], v[72:73] op_sel_hi:[1,0]
	v_pk_mul_f32 v[118:119], v[60:61], v[72:73] op_sel_hi:[1,0]
	v_pk_fma_f32 v[84:85], v[92:93], v[80:81], v[84:85]
	v_pk_fma_f32 v[112:113], v[118:119], v[82:83], v[112:113]
	v_cvt_f32_f16_e32 v80, v86
	v_cvt_f32_f16_sdwa v81, v86 dst_sel:DWORD dst_unused:UNUSED_PAD src0_sel:WORD_1
	v_cvt_f32_f16_e32 v82, v87
	v_cvt_f32_f16_sdwa v83, v87 dst_sel:DWORD dst_unused:UNUSED_PAD src0_sel:WORD_1
	v_cvt_f32_f16_e32 v86, v94
	v_cvt_f32_f16_e32 v92, v95
	v_cvt_f32_f16_sdwa v93, v95 dst_sel:DWORD dst_unused:UNUSED_PAD src0_sel:WORD_1
	v_cvt_f32_f16_sdwa v87, v94 dst_sel:DWORD dst_unused:UNUSED_PAD src0_sel:WORD_1
	v_pk_mul_f32 v[94:95], v[62:63], v[72:73] op_sel_hi:[1,0]
	v_pk_mul_f32 v[118:119], v[64:65], v[72:73] op_sel_hi:[1,0]
	v_pk_fma_f32 v[86:87], v[94:95], v[80:81], v[86:87]
	v_pk_fma_f32 v[92:93], v[118:119], v[82:83], v[92:93]
	v_cvt_pk_bf16_f32 v80, v96, v97
	v_cvt_pk_bf16_f32 v81, v100, v101
	v_cvt_pk_bf16_f32 v82, v102, v103
	v_cvt_pk_bf16_f32 v83, v98, v99
	global_store_dwordx4 v[70:71], v[80:83], off
	s_nop 1
	v_cvt_pk_bf16_f32 v80, v106, v107
	v_cvt_pk_bf16_f32 v81, v104, v105
	v_cvt_pk_bf16_f32 v82, v110, v111
	v_cvt_pk_bf16_f32 v83, v108, v109
	global_store_dwordx4 v[70:71], v[80:83], off offset:1024
	s_nop 1
	v_cvt_pk_bf16_f32 v80, v88, v89
	v_cvt_pk_bf16_f32 v81, v116, v117
	v_cvt_pk_bf16_f32 v82, v90, v91
	v_cvt_pk_bf16_f32 v83, v114, v115
	global_store_dwordx4 v[70:71], v[80:83], off offset:2048
	s_nop 1
	v_cvt_pk_bf16_f32 v80, v84, v85
	v_cvt_pk_bf16_f32 v81, v112, v113
	v_cvt_pk_bf16_f32 v82, v86, v87
	v_cvt_pk_bf16_f32 v83, v92, v93
	global_store_dwordx4 v[70:71], v[80:83], off offset:3072
	s_cmp_lt_i32 s14, 0
	s_cbranch_scc0 .Lnorm_nodefer_0
	s_waitcnt vmcnt(4)
	v_cvt_f32_f16_e32 v4, v9
	v_cvt_f32_f16_e32 v2, v8
	v_cvt_f32_f16_sdwa v5, v9 dst_sel:DWORD dst_unused:UNUSED_PAD src0_sel:WORD_1
	v_cvt_f32_f16_sdwa v3, v8 dst_sel:DWORD dst_unused:UNUSED_PAD src0_sel:WORD_1
	v_cvt_f32_f16_e32 v8, v11
	v_cvt_f32_f16_e32 v6, v10
	v_cvt_f32_f16_sdwa v9, v11 dst_sel:DWORD dst_unused:UNUSED_PAD src0_sel:WORD_1
	v_cvt_f32_f16_sdwa v7, v10 dst_sel:DWORD dst_unused:UNUSED_PAD src0_sel:WORD_1
	v_cvt_f32_f16_e32 v12, v17
	v_cvt_f32_f16_e32 v10, v16
	v_cvt_f32_f16_sdwa v13, v17 dst_sel:DWORD dst_unused:UNUSED_PAD src0_sel:WORD_1
	v_cvt_f32_f16_sdwa v11, v16 dst_sel:DWORD dst_unused:UNUSED_PAD src0_sel:WORD_1
	v_cvt_f32_f16_e32 v16, v19
	v_cvt_f32_f16_e32 v14, v18
	v_cvt_f32_f16_sdwa v17, v19 dst_sel:DWORD dst_unused:UNUSED_PAD src0_sel:WORD_1
	v_cvt_f32_f16_sdwa v15, v18 dst_sel:DWORD dst_unused:UNUSED_PAD src0_sel:WORD_1
	v_cvt_f32_f16_e32 v20, v25
	v_cvt_f32_f16_e32 v18, v24
	v_cvt_f32_f16_sdwa v21, v25 dst_sel:DWORD dst_unused:UNUSED_PAD src0_sel:WORD_1
	v_cvt_f32_f16_sdwa v19, v24 dst_sel:DWORD dst_unused:UNUSED_PAD src0_sel:WORD_1
	v_cvt_f32_f16_e32 v24, v27
	v_cvt_f32_f16_e32 v22, v26
	v_cvt_f32_f16_sdwa v25, v27 dst_sel:DWORD dst_unused:UNUSED_PAD src0_sel:WORD_1
	v_cvt_f32_f16_sdwa v23, v26 dst_sel:DWORD dst_unused:UNUSED_PAD src0_sel:WORD_1
	v_cvt_f32_f16_e32 v28, v121
	v_cvt_f32_f16_e32 v26, v120
	v_cvt_f32_f16_sdwa v29, v121 dst_sel:DWORD dst_unused:UNUSED_PAD src0_sel:WORD_1
	v_cvt_f32_f16_sdwa v27, v120 dst_sel:DWORD dst_unused:UNUSED_PAD src0_sel:WORD_1
	v_cvt_f32_f16_e32 v32, v123
	v_cvt_f32_f16_e32 v30, v122
	v_cvt_f32_f16_sdwa v33, v123 dst_sel:DWORD dst_unused:UNUSED_PAD src0_sel:WORD_1
	v_cvt_f32_f16_sdwa v31, v122 dst_sel:DWORD dst_unused:UNUSED_PAD src0_sel:WORD_1
.Lnorm_nodefer_0:
	s_cmp_lt_i32 s8, 0
	s_cbranch_scc1 .LBB0_466
	s_lshl_b64 s[0:1], s[8:9], 12
	v_cvt_pk_f16_f32 v81, v36, v37
	v_cvt_pk_f16_f32 v80, v34, v35
	v_cvt_pk_f16_f32 v82, v38, v39
	v_lshl_add_u64 v[38:39], v[68:69], 0, s[0:1]
	v_cvt_pk_f16_f32 v35, v44, v45
	v_cvt_pk_f16_f32 v34, v42, v43
	v_cvt_pk_f16_f32 v37, v48, v49
	v_cvt_pk_f16_f32 v36, v46, v47
	global_store_dwordx4 v[38:39], v[34:37], off offset:1024
	v_cvt_pk_f16_f32 v83, v40, v41
	global_store_dwordx4 v[38:39], v[80:83], off
	v_cvt_pk_f16_f32 v35, v52, v53
	v_cvt_pk_f16_f32 v34, v50, v51
	v_cvt_pk_f16_f32 v37, v56, v57
	v_cvt_pk_f16_f32 v36, v54, v55
	global_store_dwordx4 v[38:39], v[34:37], off offset:2048
	s_nop 1
	v_cvt_pk_f16_f32 v35, v60, v61
	v_cvt_pk_f16_f32 v34, v58, v59
	v_cvt_pk_f16_f32 v37, v64, v65
	v_cvt_pk_f16_f32 v36, v62, v63
	global_store_dwordx4 v[38:39], v[34:37], off offset:3072
	s_branch .LBB0_466

; __device__ __forceinline__ void lds_barrier() { asm volatile("s_waitcnt lgkmcnt(0)" ::: "memory"); __builtin_amdgcn_s_barrier(); asm volatile("" ::: "memory"); }
; template <bool COMBINE, bool SRC_F32>
; __device__ __forceinline__ void norm_phase(LAS unsigned char* lds, const void* src_lat, const void* src_ctx, _Float16* xw_ctx, const float* part, int nrows, const float* g, const float* modl, int shift_idx, int scale_idx, bf16* HN, int tid, int lane, int wave) {
;     ...
;     if (gw < nrows) NORM_LOAD(v, gw);
;     lds_barrier();
;     for (int row = gw; row < nrows; row += NGW) {
;         if (row + NGW < nrows) NORM_LOAD(nv, row + NGW);
.LBB0_1378:
	s_add_i32 s14, s4, s8
	s_add_i32 s0, s14, 0x4000
	s_cmpk_gt_i32 s0, 0x47ff
	s_cselect_b64 s[12:13], -1, 0
	s_and_b64 vcc, exec, s[12:13]
	s_cbranch_vccnz .LBB0_1381
	s_ashr_i32 s1, s0, 31
	s_cmpk_lt_i32 s0, 0x4000
	s_cselect_b64 s[16:17], -1, 0
	s_and_b64 vcc, s[16:17], exec
	v_readlane_b32 s16, v253, 52
	v_readlane_b32 s17, v253, 53
	s_cselect_b32 s1, s1, 0
	s_cselect_b32 s0, s0, s14
	s_cselect_b32 s15, s17, s7
	s_cselect_b32 s18, s16, s6
	s_lshl_b64 s[16:17], s[0:1], 12
	s_add_u32 s16, s18, s16
	s_addc_u32 s17, s15, s17
	v_lshlrev_b32_e32 v2, 1, v66
	global_load_dwordx4 v[8:11], v2, s[16:17]
	global_load_dwordx4 v[16:19], v2, s[16:17] offset:1024
	global_load_dwordx4 v[24:27], v2, s[16:17] offset:2048
	global_load_dwordx4 v[120:123], v2, s[16:17] offset:3072
	s_cbranch_vccnz .LBB0_1381
	s_waitcnt vmcnt(3)
	v_cvt_f32_f16_e32 v4, v9
	v_cvt_f32_f16_e32 v2, v8
	v_cvt_f32_f16_sdwa v5, v9 dst_sel:DWORD dst_unused:UNUSED_PAD src0_sel:WORD_1
	v_cvt_f32_f16_sdwa v3, v8 dst_sel:DWORD dst_unused:UNUSED_PAD src0_sel:WORD_1
	v_cvt_f32_f16_e32 v8, v11
	v_cvt_f32_f16_e32 v6, v10
	v_cvt_f32_f16_sdwa v9, v11 dst_sel:DWORD dst_unused:UNUSED_PAD src0_sel:WORD_1
	v_cvt_f32_f16_sdwa v7, v10 dst_sel:DWORD dst_unused:UNUSED_PAD src0_sel:WORD_1
	s_waitcnt vmcnt(2)
	v_cvt_f32_f16_e32 v12, v17
	v_cvt_f32_f16_e32 v10, v16
	v_cvt_f32_f16_sdwa v13, v17 dst_sel:DWORD dst_unused:UNUSED_PAD src0_sel:WORD_1
	v_cvt_f32_f16_sdwa v11, v16 dst_sel:DWORD dst_unused:UNUSED_PAD src0_sel:WORD_1
	v_cvt_f32_f16_e32 v16, v19
	v_cvt_f32_f16_e32 v14, v18
	v_cvt_f32_f16_sdwa v17, v19 dst_sel:DWORD dst_unused:UNUSED_PAD src0_sel:WORD_1
	v_cvt_f32_f16_sdwa v15, v18 dst_sel:DWORD dst_unused:UNUSED_PAD src0_sel:WORD_1
	s_waitcnt vmcnt(1)
	v_cvt_f32_f16_e32 v20, v25
	v_cvt_f32_f16_e32 v18, v24
	v_cvt_f32_f16_sdwa v21, v25 dst_sel:DWORD dst_unused:UNUSED_PAD src0_sel:WORD_1
	v_cvt_f32_f16_sdwa v19, v24 dst_sel:DWORD dst_unused:UNUSED_PAD src0_sel:WORD_1
	v_cvt_f32_f16_e32 v24, v27
	v_cvt_f32_f16_e32 v22, v26
	v_cvt_f32_f16_sdwa v25, v27 dst_sel:DWORD dst_unused:UNUSED_PAD src0_sel:WORD_1
	v_cvt_f32_f16_sdwa v23, v26 dst_sel:DWORD dst_unused:UNUSED_PAD src0_sel:WORD_1
	s_waitcnt vmcnt(0)
	v_cvt_f32_f16_e32 v28, v121
	v_cvt_f32_f16_e32 v26, v120
	v_cvt_f32_f16_sdwa v29, v121 dst_sel:DWORD dst_unused:UNUSED_PAD src0_sel:WORD_1
	v_cvt_f32_f16_sdwa v27, v120 dst_sel:DWORD dst_unused:UNUSED_PAD src0_sel:WORD_1
	v_cvt_f32_f16_e32 v32, v123
	v_cvt_f32_f16_e32 v30, v122
	v_cvt_f32_f16_sdwa v33, v123 dst_sel:DWORD dst_unused:UNUSED_PAD src0_sel:WORD_1
	v_cvt_f32_f16_sdwa v31, v122 dst_sel:DWORD dst_unused:UNUSED_PAD src0_sel:WORD_1
	s_lshl_b64 s[0:1], s[0:1], 11
	s_lshl_b64 s[0:1], s[0:1], 2
	v_readlane_b32 s15, v253, 54
	s_add_u32 s0, s15, s0
	v_readlane_b32 s15, v253, 56
	s_addc_u32 s1, s15, s1
	s_add_u32 s16, s0, 0x1000000
	v_lshlrev_b32_e32 v72, 2, v66
	s_addc_u32 s17, s1, 0
	global_load_dwordx4 v[80:83], v72, s[0:1] offset:16
	global_load_dwordx4 v[84:87], v72, s[0:1]
	global_load_dwordx4 v[88:91], v72, s[16:17]
	global_load_dwordx4 v[92:95], v72, s[16:17] offset:16
	global_load_dwordx4 v[96:99], v72, s[0:1] offset:2064
	global_load_dwordx4 v[100:103], v72, s[0:1] offset:2048
	global_load_dwordx4 v[104:107], v75, s[16:17]
	global_load_dwordx4 v[108:111], v75, s[16:17] offset:16
	global_load_dwordx4 v[112:115], v73, s[0:1] offset:16
	global_load_dwordx4 v[116:119], v73, s[0:1]
	global_load_dwordx4 v[120:123], v73, s[16:17]
	global_load_dwordx4 v[124:127], v73, s[16:17] offset:16
	global_load_dwordx4 v[128:131], v74, s[0:1] offset:16
	global_load_dwordx4 v[132:135], v74, s[0:1]
	global_load_dwordx4 v[136:139], v74, s[16:17]
	global_load_dwordx4 v[140:143], v74, s[16:17] offset:16
	s_add_u32 s0, s0, 0x2000000
	s_addc_u32 s1, s1, 0
	global_load_dwordx4 v[144:147], v72, s[0:1]
	global_load_dwordx4 v[148:151], v72, s[0:1] offset:16
	global_load_dwordx4 v[152:155], v75, s[0:1]
	global_load_dwordx4 v[156:159], v75, s[0:1] offset:16
	global_load_dwordx4 v[160:163], v73, s[0:1]
	global_load_dwordx4 v[164:167], v73, s[0:1] offset:16
	global_load_dwordx4 v[168:171], v74, s[0:1]
	global_load_dwordx4 v[172:175], v74, s[0:1] offset:16
	s_waitcnt vmcnt(20)
	v_pk_add_f32 v[82:83], v[82:83], v[94:95]
	v_pk_add_f32 v[86:87], v[86:87], v[90:91]
	v_pk_add_f32 v[84:85], v[84:85], v[88:89]
	v_pk_add_f32 v[80:81], v[80:81], v[92:93]
	s_waitcnt vmcnt(17)
	v_pk_add_f32 v[88:89], v[102:103], v[106:107]
	v_pk_add_f32 v[90:91], v[100:101], v[104:105]
	s_waitcnt vmcnt(16)
	v_pk_add_f32 v[92:93], v[98:99], v[110:111]
	v_pk_add_f32 v[94:95], v[96:97], v[108:109]
	s_waitcnt vmcnt(13)
	v_pk_add_f32 v[96:97], v[118:119], v[122:123]
	v_pk_add_f32 v[98:99], v[116:117], v[120:121]
	s_waitcnt vmcnt(12)
	v_pk_add_f32 v[100:101], v[114:115], v[126:127]
	v_pk_add_f32 v[102:103], v[112:113], v[124:125]
	s_waitcnt vmcnt(9)
	v_pk_add_f32 v[104:105], v[134:135], v[138:139]
	v_pk_add_f32 v[106:107], v[132:133], v[136:137]
	s_waitcnt vmcnt(8)
	v_pk_add_f32 v[108:109], v[130:131], v[142:143]
	v_pk_add_f32 v[110:111], v[128:129], v[140:141]
	s_waitcnt vmcnt(7)
	v_pk_add_f32 v[86:87], v[86:87], v[146:147]
	v_pk_add_f32 v[84:85], v[84:85], v[144:145]
	s_waitcnt vmcnt(6)
	v_pk_add_f32 v[82:83], v[82:83], v[150:151]
	v_pk_add_f32 v[80:81], v[80:81], v[148:149]
	s_waitcnt vmcnt(5)
	v_pk_add_f32 v[88:89], v[88:89], v[154:155]
	v_pk_add_f32 v[90:91], v[90:91], v[152:153]
	s_waitcnt vmcnt(4)
	v_pk_add_f32 v[92:93], v[92:93], v[158:159]
	v_pk_add_f32 v[94:95], v[94:95], v[156:157]
	s_waitcnt vmcnt(3)
	v_pk_add_f32 v[96:97], v[96:97], v[162:163]
	v_pk_add_f32 v[98:99], v[98:99], v[160:161]
	s_waitcnt vmcnt(2)
	v_pk_add_f32 v[100:101], v[100:101], v[166:167]
	v_pk_add_f32 v[102:103], v[102:103], v[164:165]
	s_waitcnt vmcnt(1)
	v_pk_add_f32 v[104:105], v[104:105], v[170:171]
	v_pk_add_f32 v[106:107], v[106:107], v[168:169]
	s_waitcnt vmcnt(0)
	v_pk_add_f32 v[108:109], v[108:109], v[174:175]
	v_pk_add_f32 v[110:111], v[110:111], v[172:173]
	v_pk_add_f32 v[4:5], v[86:87], v[4:5]
	v_pk_add_f32 v[2:3], v[84:85], v[2:3]
	v_pk_add_f32 v[8:9], v[82:83], v[8:9]
	v_pk_add_f32 v[6:7], v[80:81], v[6:7]
	v_pk_add_f32 v[12:13], v[88:89], v[12:13]
	v_pk_add_f32 v[10:11], v[90:91], v[10:11]
	v_pk_add_f32 v[16:17], v[92:93], v[16:17]
	v_pk_add_f32 v[14:15], v[94:95], v[14:15]
	v_pk_add_f32 v[20:21], v[96:97], v[20:21]
	v_pk_add_f32 v[18:19], v[98:99], v[18:19]
	v_pk_add_f32 v[24:25], v[100:101], v[24:25]
	v_pk_add_f32 v[22:23], v[102:103], v[22:23]
	v_pk_add_f32 v[28:29], v[104:105], v[28:29]
	v_pk_add_f32 v[26:27], v[106:107], v[26:27]
	v_pk_add_f32 v[32:33], v[108:109], v[32:33]
	v_pk_add_f32 v[30:31], v[110:111], v[30:31]
; #define LAS __attribute__((address_space(3)))
; __device__ __forceinline__ f32x4 h4_to_f32x4(u32x2 v) { return __builtin_convertvector(__builtin_bit_cast(f16x4, v), f32x4); }
; template <bool COMBINE, bool SRC_F32>
; __device__ __forceinline__ void norm_phase(LAS unsigned char* lds, const void* src_lat, const void* src_ctx, _Float16* xw_ctx, const float* part, int nrows, const float* g, const float* modl, int shift_idx, int scale_idx, bf16* HN, int tid, int lane, int wave) {
;     ...
;         const int r = row < M_LAT ? (row >> 11) : 8;
;         float ss = 0.f;
; #pragma unroll
;         for (int j = 0; j < 8; ++j) ss += (v[j][0] * v[j][0] + v[j][1] * v[j][1]) + (v[j][2] * v[j][2] + v[j][3] * v[j][3]);
;         const float rstd = 1.0f / sqrtf(wave_sum_dpp(ss) * (1.0f / D) + EPS);
;         bf16* o = HN + (size_t)row * D;
;         f32x4 y[8];
; #pragma unroll
;         for (int j = 0; j < 8; ++j) { const int c = NORM_COL(j); y[j] = (v[j] * rstd) * h4_to_f32x4(*(const LAS u32x2*)(Gs + r * D + c)) + h4_to_f32x4(*(const LAS u32x2*)(Ss + r * D + c)); }
.LBB0_1381:
	v_mul_f32_e32 v72, v35, v35
	v_mul_f32_e32 v79, v37, v37
	v_fmac_f32_e32 v72, v34, v34
	v_fmac_f32_e32 v79, v36, v36
	v_add_f32_e32 v72, v72, v79
	v_mul_f32_e32 v79, v39, v39
	v_mul_f32_e32 v80, v41, v41
	v_fmac_f32_e32 v79, v38, v38
	v_fmac_f32_e32 v80, v40, v40
	v_add_f32_e32 v79, v79, v80
	v_add_f32_e32 v72, v72, v79
	v_mul_f32_e32 v79, v43, v43
	v_mul_f32_e32 v80, v45, v45
	v_fmac_f32_e32 v79, v42, v42
	v_fmac_f32_e32 v80, v44, v44
	v_add_f32_e32 v79, v79, v80
	v_add_f32_e32 v72, v79, v72
	v_mul_f32_e32 v79, v47, v47
	v_mul_f32_e32 v80, v49, v49
	v_fmac_f32_e32 v79, v46, v46
	v_fmac_f32_e32 v80, v48, v48
	v_add_f32_e32 v79, v79, v80
	v_add_f32_e32 v72, v79, v72
	v_mul_f32_e32 v79, v51, v51
	v_mul_f32_e32 v80, v53, v53
	v_fmac_f32_e32 v79, v50, v50
	v_fmac_f32_e32 v80, v52, v52
	v_add_f32_e32 v79, v79, v80
	v_add_f32_e32 v72, v79, v72
	v_mul_f32_e32 v79, v55, v55
	v_mul_f32_e32 v80, v57, v57
	v_fmac_f32_e32 v79, v54, v54
	v_fmac_f32_e32 v80, v56, v56
	v_add_f32_e32 v79, v79, v80
	v_add_f32_e32 v72, v79, v72
	v_mul_f32_e32 v79, v59, v59
	v_mul_f32_e32 v80, v61, v61
	v_fmac_f32_e32 v79, v58, v58
	v_fmac_f32_e32 v80, v60, v60
	v_add_f32_e32 v79, v79, v80
	v_add_f32_e32 v72, v79, v72
	v_mul_f32_e32 v79, v63, v63
	v_mul_f32_e32 v80, v65, v65
	v_fmac_f32_e32 v79, v62, v62
	v_fmac_f32_e32 v80, v64, v64
	v_add_f32_e32 v79, v79, v80
	v_add_f32_e32 v72, v79, v72
	v_mov_b32_e32 v79, 0
	s_nop 0
	v_add_f32_dpp v72, v72, v72 quad_perm:[1,0,3,2] row_mask:0xf bank_mask:0xf bound_ctrl:1
	s_nop 1
	v_add_f32_dpp v72, v72, v72 quad_perm:[2,3,0,1] row_mask:0xf bank_mask:0xf bound_ctrl:1
	s_nop 1
	v_add_f32_dpp v72, v72, v72 row_half_mirror row_mask:0xf bank_mask:0xf bound_ctrl:1
	s_nop 1
	v_add_f32_dpp v72, v72, v72 row_mirror row_mask:0xf bank_mask:0xf bound_ctrl:1
	s_nop 1
	v_mov_b32_dpp v79, v72 row_bcast:15 row_mask:0xa bank_mask:0xf
	v_add_f32_e32 v72, v72, v79
	v_mov_b32_e32 v79, 0
	s_nop 1
	v_mov_b32_dpp v79, v72 row_bcast:31 row_mask:0xc bank_mask:0xf
	v_add_f32_e32 v72, v72, v79
	s_nop 0
	v_readlane_b32 s0, v72, 63
	s_nop 1
	v_fma_f32 v72, s0, v78, v76
	v_mul_f32_e32 v79, 0x4f800000, v72
	v_cmp_gt_f32_e32 vcc, s5, v72
	s_nop 1
	v_cndmask_b32_e32 v72, v72, v79, vcc
	v_sqrt_f32_e32 v79, v72
	s_nop 0
	v_add_u32_e32 v80, -1, v79
	v_fma_f32 v81, -v80, v79, v72
	v_cmp_ge_f32_e64 s[0:1], 0, v81
	v_add_u32_e32 v81, 1, v79
	s_nop 0
	v_cndmask_b32_e64 v80, v79, v80, s[0:1]
	v_fma_f32 v79, -v81, v79, v72
	v_cmp_lt_f32_e64 s[0:1], 0, v79
	s_nop 1
	v_cndmask_b32_e64 v79, v80, v81, s[0:1]
	v_mul_f32_e32 v80, 0x37800000, v79
	v_cndmask_b32_e32 v79, v79, v80, vcc
	v_cmp_class_f32_e32 vcc, v72, v77
	s_nop 1
	v_cndmask_b32_e32 v72, v79, v72, vcc
	v_div_scale_f32 v79, s[0:1], v72, v72, 1.0
	v_rcp_f32_e32 v84, v79
	s_add_i32 s0, s8, 0x4000
	s_min_i32 s1, s0, 0x4000
	s_and_b32 s1, s1, 0x7ffff800
	v_fma_f32 v80, -v79, v84, 1.0
	v_fmac_f32_e32 v84, v80, v84
	v_div_scale_f32 v80, vcc, 1.0, v72, 1.0
	v_mul_f32_e32 v85, v80, v84
	v_fma_f32 v81, -v79, v85, v80
	v_fmac_f32_e32 v85, v81, v84
	v_lshl_add_u32 v114, s1, 1, v67
	v_fma_f32 v79, -v79, v85, v80
	ds_read_b128 v[80:83], v114
	ds_read_b128 v[88:91], v114 offset:36864
	ds_read_b128 v[92:95], v114 offset:37888
	v_div_fmas_f32 v79, v79, v84, v85
	ds_read_b128 v[84:87], v114 offset:1024
	s_waitcnt lgkmcnt(3)
	v_cvt_f32_f16_e32 v96, v80
	v_cvt_f32_f16_sdwa v97, v80 dst_sel:DWORD dst_unused:UNUSED_PAD src0_sel:WORD_1
	v_cvt_f32_f16_e32 v80, v81
	v_cvt_f32_f16_sdwa v81, v81 dst_sel:DWORD dst_unused:UNUSED_PAD src0_sel:WORD_1
	s_waitcnt lgkmcnt(2)
	v_cvt_f32_f16_e32 v98, v88
	v_cvt_f32_f16_e32 v100, v89
	v_cvt_f32_f16_sdwa v101, v89 dst_sel:DWORD dst_unused:UNUSED_PAD src0_sel:WORD_1
	v_cvt_f32_f16_sdwa v99, v88 dst_sel:DWORD dst_unused:UNUSED_PAD src0_sel:WORD_1
	v_div_fixup_f32 v72, v79, v72, 1.0
	v_pk_mul_f32 v[88:89], v[34:35], v[72:73] op_sel_hi:[1,0]
	v_pk_mul_f32 v[102:103], v[36:37], v[72:73] op_sel_hi:[1,0]
	v_pk_fma_f32 v[96:97], v[88:89], v[96:97], v[98:99]
	v_pk_fma_f32 v[100:101], v[102:103], v[80:81], v[100:101]
	v_cvt_f32_f16_e32 v80, v82
	v_cvt_f32_f16_sdwa v81, v82 dst_sel:DWORD dst_unused:UNUSED_PAD src0_sel:WORD_1
	v_cvt_f32_f16_e32 v82, v83
	v_cvt_f32_f16_sdwa v83, v83 dst_sel:DWORD dst_unused:UNUSED_PAD src0_sel:WORD_1
	v_cvt_f32_f16_e32 v88, v90
	v_cvt_f32_f16_e32 v98, v91
	v_cvt_f32_f16_sdwa v99, v91 dst_sel:DWORD dst_unused:UNUSED_PAD src0_sel:WORD_1
	v_cvt_f32_f16_sdwa v89, v90 dst_sel:DWORD dst_unused:UNUSED_PAD src0_sel:WORD_1
	v_pk_mul_f32 v[90:91], v[38:39], v[72:73] op_sel_hi:[1,0]
	v_pk_mul_f32 v[102:103], v[40:41], v[72:73] op_sel_hi:[1,0]
	v_pk_mul_f32 v[118:119], v[52:53], v[72:73] op_sel_hi:[1,0]
	v_pk_fma_f32 v[98:99], v[102:103], v[82:83], v[98:99]
	v_pk_fma_f32 v[102:103], v[90:91], v[80:81], v[88:89]
	s_waitcnt lgkmcnt(0)
	v_cvt_f32_f16_e32 v80, v84
	v_cvt_f32_f16_sdwa v81, v84 dst_sel:DWORD dst_unused:UNUSED_PAD src0_sel:WORD_1
	v_cvt_f32_f16_e32 v82, v85
	v_cvt_f32_f16_sdwa v83, v85 dst_sel:DWORD dst_unused:UNUSED_PAD src0_sel:WORD_1
	v_cvt_f32_f16_e32 v84, v92
	v_cvt_f32_f16_e32 v88, v93
	v_cvt_f32_f16_sdwa v89, v93 dst_sel:DWORD dst_unused:UNUSED_PAD src0_sel:WORD_1
	v_cvt_f32_f16_sdwa v85, v92 dst_sel:DWORD dst_unused:UNUSED_PAD src0_sel:WORD_1
	v_pk_mul_f32 v[90:91], v[42:43], v[72:73] op_sel_hi:[1,0]
	v_pk_mul_f32 v[92:93], v[44:45], v[72:73] op_sel_hi:[1,0]
	s_cmpk_lt_i32 s0, 0x4000
	v_pk_fma_f32 v[104:105], v[92:93], v[82:83], v[88:89]
	v_pk_fma_f32 v[106:107], v[90:91], v[80:81], v[84:85]
	v_cvt_f32_f16_e32 v88, v86
	v_cvt_f32_f16_sdwa v89, v86 dst_sel:DWORD dst_unused:UNUSED_PAD src0_sel:WORD_1
	v_cvt_f32_f16_e32 v90, v94
	v_cvt_f32_f16_sdwa v91, v94 dst_sel:DWORD dst_unused:UNUSED_PAD src0_sel:WORD_1
	v_pk_mul_f32 v[84:85], v[46:47], v[72:73] op_sel_hi:[1,0]
	ds_read_b128 v[80:83], v114 offset:2048
	v_cvt_f32_f16_e32 v86, v87
	v_pk_fma_f32 v[110:111], v[84:85], v[88:89], v[90:91]
	ds_read_b128 v[88:91], v114 offset:38912
	v_cvt_f32_f16_sdwa v87, v87 dst_sel:DWORD dst_unused:UNUSED_PAD src0_sel:WORD_1
	v_cvt_f32_f16_e32 v92, v95
	v_cvt_f32_f16_sdwa v93, v95 dst_sel:DWORD dst_unused:UNUSED_PAD src0_sel:WORD_1
	v_pk_mul_f32 v[94:95], v[48:49], v[72:73] op_sel_hi:[1,0]
	s_nop 0
	v_pk_fma_f32 v[108:109], v[94:95], v[86:87], v[92:93]
	ds_read_b128 v[84:87], v114 offset:3072
	s_waitcnt lgkmcnt(2)
; __device__ __forceinline__ unsigned cvt_pk_bf16(float lo, float hi) { unsigned r; asm volatile("v_cvt_pk_bf16_f32 %0, %1, %2" : "=v"(r) : "v"(lo), "v"(hi)); return r; }
; #define LAS __attribute__((address_space(3)))
; __device__ __forceinline__ f32x4 h4_to_f32x4(u32x2 v) { return __builtin_convertvector(__builtin_bit_cast(f16x4, v), f32x4); }
; template <bool COMBINE, bool SRC_F32>
; __device__ __forceinline__ void norm_phase(LAS unsigned char* lds, const void* src_lat, const void* src_ctx, _Float16* xw_ctx, const float* part, int nrows, const float* g, const float* modl, int shift_idx, int scale_idx, bf16* HN, int tid, int lane, int wave) {
;     ...
;         for (int j = 0; j < 8; ++j) { const int c = NORM_COL(j); y[j] = (v[j] * rstd) * h4_to_f32x4(*(const LAS u32x2*)(Gs + r * D + c)) + h4_to_f32x4(*(const LAS u32x2*)(Ss + r * D + c)); }
;         if constexpr (SRC_F32) {
; #pragma unroll
;             for (int j = 0; j < 8; ++j) { u32x2 w; w.x = pg8::cvt_pk_bf16(y[j][0], y[j][1]); w.y = pg8::cvt_pk_bf16(y[j][2], y[j][3]); *(u32x2*)(o + NORM_COL(j)) = w; }
;         } else {
; #pragma unroll
;             for (int j = 0; j < 4; ++j) { u32x4 w; w.x = pg8::cvt_pk_bf16(y[2 * j][0], y[2 * j][1]); w.y = pg8::cvt_pk_bf16(y[2 * j][2], y[2 * j][3]); w.z = pg8::cvt_pk_bf16(y[2 * j + 1][0], y[2 * j + 1][1]); w.w = pg8::cvt_pk_bf16(y[2 * j + 1][2], y[2 * j + 1][3]);
;                 *(u32x4*)(o + NORM_COL(2 * j)) = w; }
	v_cvt_f32_f16_e32 v112, v80
	v_cvt_f32_f16_sdwa v113, v80 dst_sel:DWORD dst_unused:UNUSED_PAD src0_sel:WORD_1
	v_cvt_f32_f16_e32 v80, v81
	v_cvt_f32_f16_sdwa v81, v81 dst_sel:DWORD dst_unused:UNUSED_PAD src0_sel:WORD_1
	ds_read_b128 v[92:95], v114 offset:39936
	s_waitcnt lgkmcnt(2)
	v_cvt_f32_f16_e32 v114, v88
	v_cvt_f32_f16_e32 v116, v89
	v_cvt_f32_f16_sdwa v117, v89 dst_sel:DWORD dst_unused:UNUSED_PAD src0_sel:WORD_1
	v_cvt_f32_f16_sdwa v115, v88 dst_sel:DWORD dst_unused:UNUSED_PAD src0_sel:WORD_1
	v_pk_mul_f32 v[88:89], v[50:51], v[72:73] op_sel_hi:[1,0]
	v_pk_fma_f32 v[116:117], v[118:119], v[80:81], v[116:117]
	v_pk_fma_f32 v[88:89], v[88:89], v[112:113], v[114:115]
	v_cvt_f32_f16_e32 v80, v82
	v_cvt_f32_f16_sdwa v81, v82 dst_sel:DWORD dst_unused:UNUSED_PAD src0_sel:WORD_1
	v_cvt_f32_f16_e32 v82, v83
	v_cvt_f32_f16_sdwa v83, v83 dst_sel:DWORD dst_unused:UNUSED_PAD src0_sel:WORD_1
	v_cvt_f32_f16_e32 v112, v90
	v_cvt_f32_f16_e32 v114, v91
	v_cvt_f32_f16_sdwa v115, v91 dst_sel:DWORD dst_unused:UNUSED_PAD src0_sel:WORD_1
	v_cvt_f32_f16_sdwa v113, v90 dst_sel:DWORD dst_unused:UNUSED_PAD src0_sel:WORD_1
	v_pk_mul_f32 v[90:91], v[54:55], v[72:73] op_sel_hi:[1,0]
	v_pk_mul_f32 v[118:119], v[56:57], v[72:73] op_sel_hi:[1,0]
	v_pk_fma_f32 v[90:91], v[90:91], v[80:81], v[112:113]
	v_pk_fma_f32 v[114:115], v[118:119], v[82:83], v[114:115]
	s_waitcnt lgkmcnt(1)
	v_cvt_f32_f16_e32 v80, v84
	v_cvt_f32_f16_sdwa v81, v84 dst_sel:DWORD dst_unused:UNUSED_PAD src0_sel:WORD_1
	v_cvt_f32_f16_e32 v82, v85
	v_cvt_f32_f16_sdwa v83, v85 dst_sel:DWORD dst_unused:UNUSED_PAD src0_sel:WORD_1
	s_waitcnt lgkmcnt(0)
	v_cvt_f32_f16_e32 v84, v92
	v_cvt_f32_f16_e32 v112, v93
	v_cvt_f32_f16_sdwa v113, v93 dst_sel:DWORD dst_unused:UNUSED_PAD src0_sel:WORD_1
	v_cvt_f32_f16_sdwa v85, v92 dst_sel:DWORD dst_unused:UNUSED_PAD src0_sel:WORD_1
	v_pk_mul_f32 v[92:93], v[58:59], v[72:73] op_sel_hi:[1,0]
	v_pk_mul_f32 v[118:119], v[60:61], v[72:73] op_sel_hi:[1,0]
	v_pk_fma_f32 v[84:85], v[92:93], v[80:81], v[84:85]
	v_pk_fma_f32 v[112:113], v[118:119], v[82:83], v[112:113]
	v_cvt_f32_f16_e32 v80, v86
	v_cvt_f32_f16_sdwa v81, v86 dst_sel:DWORD dst_unused:UNUSED_PAD src0_sel:WORD_1
	v_cvt_f32_f16_e32 v82, v87
	v_cvt_f32_f16_sdwa v83, v87 dst_sel:DWORD dst_unused:UNUSED_PAD src0_sel:WORD_1
	v_cvt_f32_f16_e32 v86, v94
	v_cvt_f32_f16_e32 v92, v95
	v_cvt_f32_f16_sdwa v93, v95 dst_sel:DWORD dst_unused:UNUSED_PAD src0_sel:WORD_1
	v_cvt_f32_f16_sdwa v87, v94 dst_sel:DWORD dst_unused:UNUSED_PAD src0_sel:WORD_1
	v_pk_mul_f32 v[94:95], v[62:63], v[72:73] op_sel_hi:[1,0]
	v_pk_mul_f32 v[118:119], v[64:65], v[72:73] op_sel_hi:[1,0]
	v_pk_fma_f32 v[86:87], v[94:95], v[80:81], v[86:87]
	v_pk_fma_f32 v[92:93], v[118:119], v[82:83], v[92:93]
	v_cvt_pk_bf16_f32 v80, v96, v97
	v_cvt_pk_bf16_f32 v81, v100, v101
	v_cvt_pk_bf16_f32 v82, v102, v103
	v_cvt_pk_bf16_f32 v83, v98, v99
	global_store_dwordx4 v[70:71], v[80:83], off
	s_nop 1
	v_cvt_pk_bf16_f32 v80, v106, v107
	v_cvt_pk_bf16_f32 v81, v104, v105
	v_cvt_pk_bf16_f32 v82, v110, v111
	v_cvt_pk_bf16_f32 v83, v108, v109
	global_store_dwordx4 v[70:71], v[80:83], off offset:1024
	s_nop 1
	v_cvt_pk_bf16_f32 v80, v88, v89
	v_cvt_pk_bf16_f32 v81, v116, v117
	v_cvt_pk_bf16_f32 v82, v90, v91
	v_cvt_pk_bf16_f32 v83, v114, v115
	global_store_dwordx4 v[70:71], v[80:83], off offset:2048
	s_nop 1
	v_cvt_pk_bf16_f32 v80, v84, v85
	v_cvt_pk_bf16_f32 v81, v112, v113
	v_cvt_pk_bf16_f32 v82, v86, v87
	v_cvt_pk_bf16_f32 v83, v92, v93
	global_store_dwordx4 v[70:71], v[80:83], off offset:3072
	s_cmp_lt_i32 s14, 0
	s_cbranch_scc0 .Lnorm_nodefer_2
	s_waitcnt vmcnt(4)
	v_cvt_f32_f16_e32 v4, v9
	v_cvt_f32_f16_e32 v2, v8
	v_cvt_f32_f16_sdwa v5, v9 dst_sel:DWORD dst_unused:UNUSED_PAD src0_sel:WORD_1
	v_cvt_f32_f16_sdwa v3, v8 dst_sel:DWORD dst_unused:UNUSED_PAD src0_sel:WORD_1
	v_cvt_f32_f16_e32 v8, v11
	v_cvt_f32_f16_e32 v6, v10
	v_cvt_f32_f16_sdwa v9, v11 dst_sel:DWORD dst_unused:UNUSED_PAD src0_sel:WORD_1
	v_cvt_f32_f16_sdwa v7, v10 dst_sel:DWORD dst_unused:UNUSED_PAD src0_sel:WORD_1
	v_cvt_f32_f16_e32 v12, v17
	v_cvt_f32_f16_e32 v10, v16
	v_cvt_f32_f16_sdwa v13, v17 dst_sel:DWORD dst_unused:UNUSED_PAD src0_sel:WORD_1
	v_cvt_f32_f16_sdwa v11, v16 dst_sel:DWORD dst_unused:UNUSED_PAD src0_sel:WORD_1
	v_cvt_f32_f16_e32 v16, v19
	v_cvt_f32_f16_e32 v14, v18
	v_cvt_f32_f16_sdwa v17, v19 dst_sel:DWORD dst_unused:UNUSED_PAD src0_sel:WORD_1
	v_cvt_f32_f16_sdwa v15, v18 dst_sel:DWORD dst_unused:UNUSED_PAD src0_sel:WORD_1
	v_cvt_f32_f16_e32 v20, v25
	v_cvt_f32_f16_e32 v18, v24
	v_cvt_f32_f16_sdwa v21, v25 dst_sel:DWORD dst_unused:UNUSED_PAD src0_sel:WORD_1
	v_cvt_f32_f16_sdwa v19, v24 dst_sel:DWORD dst_unused:UNUSED_PAD src0_sel:WORD_1
	v_cvt_f32_f16_e32 v24, v27
	v_cvt_f32_f16_e32 v22, v26
	v_cvt_f32_f16_sdwa v25, v27 dst_sel:DWORD dst_unused:UNUSED_PAD src0_sel:WORD_1
	v_cvt_f32_f16_sdwa v23, v26 dst_sel:DWORD dst_unused:UNUSED_PAD src0_sel:WORD_1
	v_cvt_f32_f16_e32 v28, v121
	v_cvt_f32_f16_e32 v26, v120
	v_cvt_f32_f16_sdwa v29, v121 dst_sel:DWORD dst_unused:UNUSED_PAD src0_sel:WORD_1
	v_cvt_f32_f16_sdwa v27, v120 dst_sel:DWORD dst_unused:UNUSED_PAD src0_sel:WORD_1
	v_cvt_f32_f16_e32 v32, v123
	v_cvt_f32_f16_e32 v30, v122
	v_cvt_f32_f16_sdwa v33, v123 dst_sel:DWORD dst_unused:UNUSED_PAD src0_sel:WORD_1
	v_cvt_f32_f16_sdwa v31, v122 dst_sel:DWORD dst_unused:UNUSED_PAD src0_sel:WORD_1
